# SwiGLU epilogue: store addresses for row groups 1-7 derived from group-0 address plus constant (drops mad_i64 + 2 u64 adds per group)
# speedup vs baseline: 1.0058x; 1.0058x over previous
.Lz_post_p1:
	s_lshl_b32 s25, s46, 8
	v_add_u32_e32 v148, s25, v150
	v_ashrrev_i32_e32 v149, 31, v148
	v_lshl_add_u64 v[244:245], v[148:149], 2, s[8:9]
	global_load_dword v149, v[244:245], off
	global_load_dword v232, v[244:245], off offset:64
	global_load_dword v233, v[244:245], off offset:128
	global_load_dword v234, v[244:245], off offset:192
	global_load_dword v235, v[244:245], off offset:512
	global_load_dword v236, v[244:245], off offset:576
	global_load_dword v237, v[244:245], off offset:640
	global_load_dword v238, v[244:245], off offset:704
	v_pk_mul_f32 v[128:129], v[120:121], v[128:129]
	v_pk_mul_f32 v[126:127], v[118:119], v[126:127]
	v_pk_mul_f32 v[124:125], v[116:117], v[124:125]
	v_pk_mul_f32 v[244:245], v[114:115], v[122:123]
	s_lshl_b32 s46, s47, 7
	v_mov_b64_e32 v[122:123], s[12:13]
	s_ashr_i32 s47, s46, 31
	v_mad_i64_i32 v[248:249], s[48:49], v148, s68, v[122:123]
	s_lshl_b64 s[46:47], s[46:47], 1
	v_lshl_add_u64 v[248:249], v[248:249], 0, s[46:47]
	v_lshl_add_u64 v[248:249], v[248:249], 0, v[138:139]
	v_mov_b64_e32 v[240:241], v[248:249]
	s_mov_b32 s99, 0
	v_pk_mul_f32 v[112:113], v[108:109], v[112:113]
	v_pk_mul_f32 v[110:111], v[106:107], v[110:111]
	v_pk_mul_f32 v[104:105], v[100:101], v[104:105]
	v_pk_mul_f32 v[102:103], v[98:99], v[102:103]
	v_pk_mul_f32 v[96:97], v[92:93], v[96:97]
	v_pk_mul_f32 v[94:95], v[90:91], v[94:95]
	v_pk_mul_f32 v[88:89], v[84:85], v[88:89]
	v_pk_mul_f32 v[86:87], v[82:83], v[86:87]
	v_pk_mul_f32 v[80:81], v[76:77], v[80:81]
	v_pk_mul_f32 v[78:79], v[74:75], v[78:79]
	v_pk_mul_f32 v[72:73], v[68:69], v[72:73]
	v_pk_mul_f32 v[70:71], v[66:67], v[70:71]
	v_pk_mul_f32 v[64:65], v[60:61], v[64:65]
	v_pk_mul_f32 v[62:63], v[58:59], v[62:63]
	v_pk_mul_f32 v[56:57], v[52:53], v[56:57]
	v_pk_mul_f32 v[54:55], v[50:51], v[54:55]
	v_pk_mul_f32 v[48:49], v[44:45], v[48:49]
	v_pk_mul_f32 v[46:47], v[42:43], v[46:47]
	v_pk_mul_f32 v[40:41], v[36:37], v[40:41]
	v_pk_mul_f32 v[38:39], v[34:35], v[38:39]
	v_pk_mul_f32 v[32:33], v[28:29], v[32:33]
	v_pk_mul_f32 v[30:31], v[26:27], v[30:31]
	v_pk_mul_f32 v[24:25], v[20:21], v[24:25]
	v_pk_mul_f32 v[22:23], v[18:19], v[22:23]
	v_pk_mul_f32 v[16:17], v[12:13], v[16:17]
	v_pk_mul_f32 v[14:15], v[10:11], v[14:15]
	v_pk_mul_f32 v[4:5], v[8:9], v[4:5]
	v_pk_mul_f32 v[2:3], v[6:7], v[2:3]
	s_and_b64 vcc, exec, s[16:17]
	s_cbranch_vccz .LBB0_155
	s_barrier
.LBB0_155:
	ds_read_b128 v[160:163], v155
	ds_read_b128 v[164:167], v155 offset:1024
	ds_read_b128 v[168:171], v155 offset:2048
	ds_read_b128 v[172:175], v155 offset:3072
	ds_read_b128 v[176:179], v156
	ds_read_b128 v[180:183], v156 offset:1024
	ds_read_b128 v[184:187], v156 offset:2048
	ds_read_b128 v[188:191], v156 offset:3072
	ds_read_b128 v[192:195], v157
	ds_read_b128 v[196:199], v157 offset:1024
	ds_read_b128 v[200:203], v157 offset:2048
	ds_read_b128 v[204:207], v157 offset:3072
	ds_read_b128 v[208:211], v157 offset:4096
	ds_read_b128 v[212:215], v157 offset:5120
	ds_read_b128 v[216:219], v157 offset:6144
	ds_read_b128 v[220:223], v157 offset:7168
	s_andn2_b64 vcc, exec, s[4:5]
	s_waitcnt vmcnt(0)
	v_fmamk_f32 v239, v149, 0x3a800000, v158
	v_rsq_f32_e32 v149, v239
	s_nop 0
	v_mul_f32_e32 v252, 0xbfb8aa3b, v149
	v_pk_mul_f32 v[120:121], v[120:121], v[252:253] op_sel_hi:[1,0]
	v_pk_mul_f32 v[118:119], v[118:119], v[252:253] op_sel_hi:[1,0]
	v_pk_mul_f32 v[116:117], v[116:117], v[252:253] op_sel_hi:[1,0]
	v_pk_mul_f32 v[114:115], v[114:115], v[252:253] op_sel_hi:[1,0]
	v_exp_f32_e32 v118, v118
	v_exp_f32_e32 v119, v119
	v_exp_f32_e32 v120, v120
	v_exp_f32_e32 v121, v121
	v_exp_f32_e32 v114, v114
	v_exp_f32_e32 v115, v115
	v_exp_f32_e32 v116, v116
	v_exp_f32_e32 v117, v117
	v_fma_f32 v118, v118, v239, v239
	v_fma_f32 v119, v119, v239, v239
	v_fma_f32 v120, v120, v239, v239
	v_fma_f32 v121, v121, v239, v239
	v_fma_f32 v149, v114, v239, v239
	v_fma_f32 v159, v115, v239, v239
	v_fma_f32 v247, v116, v239, v239
	v_fma_f32 v252, v117, v239, v239
	v_rcp_f32_e32 v114, v118
	v_rcp_f32_e32 v115, v119
	v_rcp_f32_e32 v116, v120
	v_rcp_f32_e32 v117, v121
	v_rcp_f32_e32 v118, v149
	v_rcp_f32_e32 v119, v159
	v_rcp_f32_e32 v120, v247
	v_rcp_f32_e32 v121, v252
	v_pk_mul_f32 v[116:117], v[128:129], v[116:117]
	v_pk_mul_f32 v[114:115], v[126:127], v[114:115]
	v_pk_mul_f32 v[120:121], v[124:125], v[120:121]
	v_pk_mul_f32 v[118:119], v[244:245], v[118:119]
	v_cvt_pk_bf16_f32 v114, v114, v115
	v_cvt_pk_bf16_f32 v115, v116, v117
	v_cvt_pk_bf16_f32 v116, v118, v119
	v_cvt_pk_bf16_f32 v117, v120, v121
	global_store_dwordx4 v[248:249], v[114:117], off
	v_fmamk_f32 v239, v232, 0x3a800000, v158
	v_rsq_f32_e32 v121, v239
	s_nop 0
	v_mul_f32_e32 v120, 0xbfb8aa3b, v121
	v_pk_mul_f32 v[108:109], v[108:109], v[120:121] op_sel_hi:[1,0]
	v_pk_mul_f32 v[106:107], v[106:107], v[120:121] op_sel_hi:[1,0]
	v_pk_mul_f32 v[100:101], v[100:101], v[120:121] op_sel_hi:[1,0]
	v_pk_mul_f32 v[98:99], v[98:99], v[120:121] op_sel_hi:[1,0]
	v_exp_f32_e32 v106, v106
	v_exp_f32_e32 v107, v107
	v_exp_f32_e32 v108, v108
	v_exp_f32_e32 v109, v109
	v_exp_f32_e32 v98, v98
	v_exp_f32_e32 v99, v99
	v_exp_f32_e32 v100, v100
	v_exp_f32_e32 v101, v101
	v_fma_f32 v106, v106, v239, v239
	v_fma_f32 v107, v107, v239, v239
	v_fma_f32 v108, v108, v239, v239
	v_fma_f32 v109, v109, v239, v239
	v_fma_f32 v115, v98, v239, v239
	v_fma_f32 v120, v99, v239, v239
	v_fma_f32 v121, v100, v239, v239
	v_fma_f32 v125, v101, v239, v239
	v_rcp_f32_e32 v98, v106
	v_rcp_f32_e32 v99, v107
	v_rcp_f32_e32 v100, v108
	v_rcp_f32_e32 v101, v109
	v_rcp_f32_e32 v106, v115
	v_rcp_f32_e32 v107, v120
	v_rcp_f32_e32 v108, v121
	v_rcp_f32_e32 v109, v125
	v_pk_mul_f32 v[100:101], v[112:113], v[100:101]
	v_pk_mul_f32 v[98:99], v[110:111], v[98:99]
	v_pk_mul_f32 v[104:105], v[104:105], v[108:109]
	v_pk_mul_f32 v[102:103], v[102:103], v[106:107]
	s_mov_b32 s98, 0x16000
	v_lshl_add_u64 v[116:117], v[240:241], 0, s[98:99]
	v_cvt_pk_bf16_f32 v98, v98, v99
	v_cvt_pk_bf16_f32 v99, v100, v101
	v_cvt_pk_bf16_f32 v100, v102, v103
	v_cvt_pk_bf16_f32 v101, v104, v105
	global_store_dwordx4 v[116:117], v[98:101], off
	v_fmamk_f32 v239, v233, 0x3a800000, v158
	v_rsq_f32_e32 v105, v239
	s_nop 0
	v_mul_f32_e32 v104, 0xbfb8aa3b, v105
	v_pk_mul_f32 v[92:93], v[92:93], v[104:105] op_sel_hi:[1,0]
	v_pk_mul_f32 v[90:91], v[90:91], v[104:105] op_sel_hi:[1,0]
	v_pk_mul_f32 v[84:85], v[84:85], v[104:105] op_sel_hi:[1,0]
	v_pk_mul_f32 v[82:83], v[82:83], v[104:105] op_sel_hi:[1,0]
	v_exp_f32_e32 v90, v90
	v_exp_f32_e32 v91, v91
	v_exp_f32_e32 v92, v92
	v_exp_f32_e32 v93, v93
	v_exp_f32_e32 v82, v82
	v_exp_f32_e32 v83, v83
	v_exp_f32_e32 v84, v84
	v_exp_f32_e32 v85, v85
	v_fma_f32 v90, v90, v239, v239
	v_fma_f32 v91, v91, v239, v239
	v_fma_f32 v92, v92, v239, v239
	v_fma_f32 v93, v93, v239, v239
	v_fma_f32 v99, v82, v239, v239
	v_fma_f32 v104, v83, v239, v239
	v_fma_f32 v105, v84, v239, v239
	v_fma_f32 v107, v85, v239, v239
	v_rcp_f32_e32 v82, v90
	v_rcp_f32_e32 v83, v91
	v_rcp_f32_e32 v84, v92
	v_rcp_f32_e32 v85, v93
	v_rcp_f32_e32 v90, v99
	v_rcp_f32_e32 v91, v104
	v_rcp_f32_e32 v92, v105
	v_rcp_f32_e32 v93, v107
	v_pk_mul_f32 v[84:85], v[96:97], v[84:85]
	v_pk_mul_f32 v[82:83], v[94:95], v[82:83]
	v_pk_mul_f32 v[88:89], v[88:89], v[92:93]
	v_pk_mul_f32 v[86:87], v[86:87], v[90:91]
	s_mov_b32 s98, 0x2c000
	v_lshl_add_u64 v[100:101], v[240:241], 0, s[98:99]
	v_cvt_pk_bf16_f32 v82, v82, v83
	v_cvt_pk_bf16_f32 v83, v84, v85
	v_cvt_pk_bf16_f32 v84, v86, v87
	v_cvt_pk_bf16_f32 v85, v88, v89
	global_store_dwordx4 v[100:101], v[82:85], off
	s_nop 0
	s_nop 0
	s_mov_b32 s98, 0x42000
	v_lshl_add_u64 v[82:83], v[240:241], 0, s[98:99]
	v_fmamk_f32 v239, v234, 0x3a800000, v158
	v_rsq_f32_e32 v89, v239
	s_nop 0
	v_mul_f32_e32 v88, 0xbfb8aa3b, v89
	v_pk_mul_f32 v[76:77], v[76:77], v[88:89] op_sel_hi:[1,0]
	v_pk_mul_f32 v[74:75], v[74:75], v[88:89] op_sel_hi:[1,0]
	v_pk_mul_f32 v[68:69], v[68:69], v[88:89] op_sel_hi:[1,0]
	v_pk_mul_f32 v[66:67], v[66:67], v[88:89] op_sel_hi:[1,0]
	v_exp_f32_e32 v74, v74
	v_exp_f32_e32 v75, v75
	v_exp_f32_e32 v76, v76
	v_exp_f32_e32 v77, v77
	v_exp_f32_e32 v66, v66
	v_exp_f32_e32 v67, v67
	v_exp_f32_e32 v68, v68
	v_exp_f32_e32 v69, v69
	v_fma_f32 v74, v74, v239, v239
	v_fma_f32 v75, v75, v239, v239
	v_fma_f32 v76, v76, v239, v239
	v_fma_f32 v77, v77, v239, v239
	v_fma_f32 v85, v66, v239, v239
	v_fma_f32 v88, v67, v239, v239
	v_fma_f32 v89, v68, v239, v239
	v_fma_f32 v91, v69, v239, v239
	v_rcp_f32_e32 v66, v74
	v_rcp_f32_e32 v67, v75
	v_rcp_f32_e32 v68, v76
	v_rcp_f32_e32 v69, v77
	v_rcp_f32_e32 v74, v85
	v_rcp_f32_e32 v75, v88
	v_rcp_f32_e32 v76, v89
	v_rcp_f32_e32 v77, v91
	v_pk_mul_f32 v[68:69], v[80:81], v[68:69]
	v_pk_mul_f32 v[66:67], v[78:79], v[66:67]
	v_pk_mul_f32 v[72:73], v[72:73], v[76:77]
	v_pk_mul_f32 v[70:71], v[70:71], v[74:75]
	v_cvt_pk_bf16_f32 v66, v66, v67
	v_cvt_pk_bf16_f32 v67, v68, v69
	v_cvt_pk_bf16_f32 v68, v70, v71
	v_cvt_pk_bf16_f32 v69, v72, v73
	global_store_dwordx4 v[82:83], v[66:69], off
	v_fmamk_f32 v239, v235, 0x3a800000, v158
	v_rsq_f32_e32 v73, v239
	s_nop 0
	v_mul_f32_e32 v72, 0xbfb8aa3b, v73
	v_pk_mul_f32 v[60:61], v[60:61], v[72:73] op_sel_hi:[1,0]
	v_pk_mul_f32 v[58:59], v[58:59], v[72:73] op_sel_hi:[1,0]
	v_pk_mul_f32 v[52:53], v[52:53], v[72:73] op_sel_hi:[1,0]
	v_pk_mul_f32 v[50:51], v[50:51], v[72:73] op_sel_hi:[1,0]
	v_exp_f32_e32 v58, v58
	v_exp_f32_e32 v59, v59
	v_exp_f32_e32 v60, v60
	v_exp_f32_e32 v61, v61
	v_exp_f32_e32 v50, v50
	v_exp_f32_e32 v51, v51
	v_exp_f32_e32 v52, v52
	v_exp_f32_e32 v53, v53
	v_fma_f32 v58, v58, v239, v239
	v_fma_f32 v59, v59, v239, v239
	v_fma_f32 v60, v60, v239, v239
	v_fma_f32 v61, v61, v239, v239
	v_fma_f32 v67, v50, v239, v239
	v_fma_f32 v72, v51, v239, v239
	v_fma_f32 v73, v52, v239, v239
	v_fma_f32 v75, v53, v239, v239
	v_rcp_f32_e32 v50, v58
	v_rcp_f32_e32 v51, v59
	v_rcp_f32_e32 v52, v60
	v_rcp_f32_e32 v53, v61
	v_rcp_f32_e32 v58, v67
	v_rcp_f32_e32 v59, v72
	v_rcp_f32_e32 v60, v73
	v_rcp_f32_e32 v61, v75
	v_pk_mul_f32 v[52:53], v[64:65], v[52:53]
	v_pk_mul_f32 v[50:51], v[62:63], v[50:51]
	v_pk_mul_f32 v[56:57], v[56:57], v[60:61]
	v_pk_mul_f32 v[54:55], v[54:55], v[58:59]
	s_mov_b32 s98, 0xb0000
	v_lshl_add_u64 v[68:69], v[240:241], 0, s[98:99]
	v_cvt_pk_bf16_f32 v50, v50, v51
	v_cvt_pk_bf16_f32 v51, v52, v53
	v_cvt_pk_bf16_f32 v52, v54, v55
	v_cvt_pk_bf16_f32 v53, v56, v57
	global_store_dwordx4 v[68:69], v[50:53], off
	v_fmamk_f32 v239, v236, 0x3a800000, v158
	v_rsq_f32_e32 v57, v239
	s_nop 0
	v_mul_f32_e32 v56, 0xbfb8aa3b, v57
	v_pk_mul_f32 v[44:45], v[44:45], v[56:57] op_sel_hi:[1,0]
	v_pk_mul_f32 v[42:43], v[42:43], v[56:57] op_sel_hi:[1,0]
	v_pk_mul_f32 v[36:37], v[36:37], v[56:57] op_sel_hi:[1,0]
	v_pk_mul_f32 v[34:35], v[34:35], v[56:57] op_sel_hi:[1,0]
	v_exp_f32_e32 v42, v42
	v_exp_f32_e32 v43, v43
	v_exp_f32_e32 v44, v44
	v_exp_f32_e32 v45, v45
	v_exp_f32_e32 v34, v34
	v_exp_f32_e32 v35, v35
	v_exp_f32_e32 v36, v36
	v_exp_f32_e32 v37, v37
	v_fma_f32 v42, v42, v239, v239
	v_fma_f32 v43, v43, v239, v239
	v_fma_f32 v44, v44, v239, v239
	v_fma_f32 v45, v45, v239, v239
	v_fma_f32 v51, v34, v239, v239
	v_fma_f32 v56, v35, v239, v239
	v_fma_f32 v57, v36, v239, v239
	v_fma_f32 v59, v37, v239, v239
	v_rcp_f32_e32 v34, v42
	v_rcp_f32_e32 v35, v43
	v_rcp_f32_e32 v36, v44
	v_rcp_f32_e32 v37, v45
	v_rcp_f32_e32 v42, v51
	v_rcp_f32_e32 v43, v56
	v_rcp_f32_e32 v44, v57
	v_rcp_f32_e32 v45, v59
	v_pk_mul_f32 v[36:37], v[48:49], v[36:37]
	v_pk_mul_f32 v[34:35], v[46:47], v[34:35]
	v_pk_mul_f32 v[40:41], v[40:41], v[44:45]
	v_pk_mul_f32 v[38:39], v[38:39], v[42:43]
	s_mov_b32 s98, 0xc6000
	v_lshl_add_u64 v[52:53], v[240:241], 0, s[98:99]
	v_cvt_pk_bf16_f32 v34, v34, v35
	v_cvt_pk_bf16_f32 v35, v36, v37
	v_cvt_pk_bf16_f32 v36, v38, v39
	v_cvt_pk_bf16_f32 v37, v40, v41
	global_store_dwordx4 v[52:53], v[34:37], off
	v_fmamk_f32 v239, v237, 0x3a800000, v158
	v_rsq_f32_e32 v41, v239
	s_nop 0
	v_mul_f32_e32 v40, 0xbfb8aa3b, v41
	v_pk_mul_f32 v[28:29], v[28:29], v[40:41] op_sel_hi:[1,0]
	v_pk_mul_f32 v[26:27], v[26:27], v[40:41] op_sel_hi:[1,0]
	v_pk_mul_f32 v[20:21], v[20:21], v[40:41] op_sel_hi:[1,0]
	v_pk_mul_f32 v[18:19], v[18:19], v[40:41] op_sel_hi:[1,0]
	v_exp_f32_e32 v26, v26
	v_exp_f32_e32 v27, v27
	v_exp_f32_e32 v28, v28
	v_exp_f32_e32 v29, v29
	v_exp_f32_e32 v18, v18
	v_exp_f32_e32 v19, v19
	v_exp_f32_e32 v20, v20
	v_exp_f32_e32 v21, v21
	v_fma_f32 v26, v26, v239, v239
	v_fma_f32 v27, v27, v239, v239
	v_fma_f32 v28, v28, v239, v239
	v_fma_f32 v29, v29, v239, v239
	v_fma_f32 v35, v18, v239, v239
	v_fma_f32 v40, v19, v239, v239
	v_fma_f32 v41, v20, v239, v239
	v_fma_f32 v43, v21, v239, v239
	v_rcp_f32_e32 v18, v26
	v_rcp_f32_e32 v19, v27
	v_rcp_f32_e32 v20, v28
	v_rcp_f32_e32 v21, v29
	v_rcp_f32_e32 v26, v35
	v_rcp_f32_e32 v27, v40
	v_rcp_f32_e32 v28, v41
	v_rcp_f32_e32 v29, v43
	v_pk_mul_f32 v[20:21], v[32:33], v[20:21]
	v_pk_mul_f32 v[18:19], v[30:31], v[18:19]
	v_pk_mul_f32 v[24:25], v[24:25], v[28:29]
	v_pk_mul_f32 v[22:23], v[22:23], v[26:27]
	s_mov_b32 s98, 0xdc000
	v_lshl_add_u64 v[36:37], v[240:241], 0, s[98:99]
	v_cvt_pk_bf16_f32 v18, v18, v19
	v_cvt_pk_bf16_f32 v19, v20, v21
	v_cvt_pk_bf16_f32 v20, v22, v23
	v_cvt_pk_bf16_f32 v21, v24, v25
	global_store_dwordx4 v[36:37], v[18:21], off
	s_nop 0
	s_nop 0
	v_fmamk_f32 v239, v238, 0x3a800000, v158
	v_rsq_f32_e32 v21, v239
	s_nop 0
	v_mul_f32_e32 v20, 0xbfb8aa3b, v21
	v_pk_mul_f32 v[12:13], v[12:13], v[20:21] op_sel_hi:[1,0]
	v_pk_mul_f32 v[10:11], v[10:11], v[20:21] op_sel_hi:[1,0]
	v_pk_mul_f32 v[8:9], v[8:9], v[20:21] op_sel_hi:[1,0]
	v_pk_mul_f32 v[6:7], v[6:7], v[20:21] op_sel_hi:[1,0]
	v_exp_f32_e32 v10, v10
	v_exp_f32_e32 v11, v11
	v_exp_f32_e32 v12, v12
	v_exp_f32_e32 v13, v13
	v_exp_f32_e32 v6, v6
	v_exp_f32_e32 v7, v7
	v_exp_f32_e32 v8, v8
	v_exp_f32_e32 v9, v9
	v_fma_f32 v10, v10, v239, v239
	v_fma_f32 v11, v11, v239, v239
	v_fma_f32 v12, v12, v239, v239
	v_fma_f32 v13, v13, v239, v239
	v_fma_f32 v20, v6, v239, v239
	v_fma_f32 v21, v7, v239, v239
	v_fma_f32 v23, v8, v239, v239
	v_fma_f32 v24, v9, v239, v239
	v_rcp_f32_e32 v6, v10
	v_rcp_f32_e32 v7, v11
	v_rcp_f32_e32 v8, v12
	v_rcp_f32_e32 v9, v13
	v_rcp_f32_e32 v10, v20
	v_rcp_f32_e32 v11, v21
	v_rcp_f32_e32 v12, v23
	v_rcp_f32_e32 v13, v24
	v_pk_mul_f32 v[8:9], v[16:17], v[8:9]
	v_pk_mul_f32 v[6:7], v[14:15], v[6:7]
	v_pk_mul_f32 v[12:13], v[4:5], v[12:13]
	v_pk_mul_f32 v[4:5], v[2:3], v[10:11]
	s_mov_b32 s98, 0xf2000
	v_lshl_add_u64 v[18:19], v[240:241], 0, s[98:99]
	v_cvt_pk_bf16_f32 v2, v6, v7
	v_cvt_pk_bf16_f32 v3, v8, v9
	v_cvt_pk_bf16_f32 v4, v4, v5
	v_cvt_pk_bf16_f32 v5, v12, v13
	s_mov_b64 s[4:5], -1
	global_store_dwordx4 v[18:19], v[2:5], off
	s_cbranch_vccnz .LBB0_148
	s_andn2_b64 vcc, exec, s[10:11]
	s_cbranch_vccnz .LBB0_147
	s_barrier
	s_branch .LBB0_147

.Lz_post_p6:
	s_lshl_b32 s25, s46, 8
	v_add_u32_e32 v148, s25, v150
	v_ashrrev_i32_e32 v149, 31, v148
	v_lshl_add_u64 v[244:245], v[148:149], 2, s[10:11]
	global_load_dword v149, v[244:245], off
	global_load_dword v232, v[244:245], off offset:64
	global_load_dword v233, v[244:245], off offset:128
	global_load_dword v234, v[244:245], off offset:192
	global_load_dword v235, v[244:245], off offset:512
	global_load_dword v236, v[244:245], off offset:576
	global_load_dword v237, v[244:245], off offset:640
	global_load_dword v238, v[244:245], off offset:704
	v_pk_mul_f32 v[128:129], v[120:121], v[128:129]
	v_pk_mul_f32 v[126:127], v[118:119], v[126:127]
	v_pk_mul_f32 v[124:125], v[116:117], v[124:125]
	v_pk_mul_f32 v[244:245], v[114:115], v[122:123]
	s_lshl_b32 s46, s47, 7
	v_mov_b64_e32 v[122:123], s[12:13]
	s_ashr_i32 s47, s46, 31
	v_mad_i64_i32 v[248:249], s[48:49], v148, s68, v[122:123]
	s_lshl_b64 s[46:47], s[46:47], 1
	v_lshl_add_u64 v[248:249], v[248:249], 0, s[46:47]
	v_lshl_add_u64 v[248:249], v[248:249], 0, v[138:139]
	v_mov_b64_e32 v[240:241], v[248:249]
	s_mov_b32 s99, 0
	v_pk_mul_f32 v[112:113], v[108:109], v[112:113]
	v_pk_mul_f32 v[110:111], v[106:107], v[110:111]
	v_pk_mul_f32 v[104:105], v[100:101], v[104:105]
	v_pk_mul_f32 v[102:103], v[98:99], v[102:103]
	v_pk_mul_f32 v[96:97], v[92:93], v[96:97]
	v_pk_mul_f32 v[94:95], v[90:91], v[94:95]
	v_pk_mul_f32 v[88:89], v[84:85], v[88:89]
	v_pk_mul_f32 v[86:87], v[82:83], v[86:87]
	v_pk_mul_f32 v[80:81], v[76:77], v[80:81]
	v_pk_mul_f32 v[78:79], v[74:75], v[78:79]
	v_pk_mul_f32 v[72:73], v[68:69], v[72:73]
	v_pk_mul_f32 v[70:71], v[66:67], v[70:71]
	v_pk_mul_f32 v[64:65], v[60:61], v[64:65]
	v_pk_mul_f32 v[62:63], v[58:59], v[62:63]
	v_pk_mul_f32 v[56:57], v[52:53], v[56:57]
	v_pk_mul_f32 v[54:55], v[50:51], v[54:55]
	v_pk_mul_f32 v[48:49], v[44:45], v[48:49]
	v_pk_mul_f32 v[46:47], v[42:43], v[46:47]
	v_pk_mul_f32 v[40:41], v[36:37], v[40:41]
	v_pk_mul_f32 v[38:39], v[34:35], v[38:39]
	v_pk_mul_f32 v[32:33], v[28:29], v[32:33]
	v_pk_mul_f32 v[30:31], v[26:27], v[30:31]
	v_pk_mul_f32 v[24:25], v[20:21], v[24:25]
	v_pk_mul_f32 v[22:23], v[18:19], v[22:23]
	v_pk_mul_f32 v[16:17], v[12:13], v[16:17]
	v_pk_mul_f32 v[14:15], v[10:11], v[14:15]
	v_pk_mul_f32 v[4:5], v[8:9], v[4:5]
	v_pk_mul_f32 v[2:3], v[6:7], v[2:3]
	s_and_b64 vcc, exec, s[16:17]
	s_cbranch_vccz .LBB0_843
	s_barrier
.LBB0_843:
	ds_read_b128 v[160:163], v155
	ds_read_b128 v[164:167], v155 offset:1024
	ds_read_b128 v[168:171], v155 offset:2048
	ds_read_b128 v[172:175], v155 offset:3072
	ds_read_b128 v[176:179], v156
	ds_read_b128 v[180:183], v156 offset:1024
	ds_read_b128 v[184:187], v156 offset:2048
	ds_read_b128 v[188:191], v156 offset:3072
	ds_read_b128 v[192:195], v157
	ds_read_b128 v[196:199], v157 offset:1024
	ds_read_b128 v[200:203], v157 offset:2048
	ds_read_b128 v[204:207], v157 offset:3072
	ds_read_b128 v[208:211], v157 offset:4096
	ds_read_b128 v[212:215], v157 offset:5120
	ds_read_b128 v[216:219], v157 offset:6144
	ds_read_b128 v[220:223], v157 offset:7168
	s_andn2_b64 vcc, exec, s[4:5]
	s_waitcnt vmcnt(0)
	v_fmamk_f32 v239, v149, 0x3a800000, v158
	v_rsq_f32_e32 v149, v239
	s_nop 0
	v_mul_f32_e32 v252, 0xbfb8aa3b, v149
	v_pk_mul_f32 v[120:121], v[120:121], v[252:253] op_sel_hi:[1,0]
	v_pk_mul_f32 v[118:119], v[118:119], v[252:253] op_sel_hi:[1,0]
	v_pk_mul_f32 v[116:117], v[116:117], v[252:253] op_sel_hi:[1,0]
	v_pk_mul_f32 v[114:115], v[114:115], v[252:253] op_sel_hi:[1,0]
	v_exp_f32_e32 v118, v118
	v_exp_f32_e32 v119, v119
	v_exp_f32_e32 v120, v120
	v_exp_f32_e32 v121, v121
	v_exp_f32_e32 v114, v114
	v_exp_f32_e32 v115, v115
	v_exp_f32_e32 v116, v116
	v_exp_f32_e32 v117, v117
	v_fma_f32 v118, v118, v239, v239
	v_fma_f32 v119, v119, v239, v239
	v_fma_f32 v120, v120, v239, v239
	v_fma_f32 v121, v121, v239, v239
	v_fma_f32 v149, v114, v239, v239
	v_fma_f32 v159, v115, v239, v239
	v_fma_f32 v247, v116, v239, v239
	v_fma_f32 v252, v117, v239, v239
	v_rcp_f32_e32 v114, v118
	v_rcp_f32_e32 v115, v119
	v_rcp_f32_e32 v116, v120
	v_rcp_f32_e32 v117, v121
	v_rcp_f32_e32 v118, v149
	v_rcp_f32_e32 v119, v159
	v_rcp_f32_e32 v120, v247
	v_rcp_f32_e32 v121, v252
	v_pk_mul_f32 v[116:117], v[128:129], v[116:117]
	v_pk_mul_f32 v[114:115], v[126:127], v[114:115]
	v_pk_mul_f32 v[120:121], v[124:125], v[120:121]
	v_pk_mul_f32 v[118:119], v[244:245], v[118:119]
	v_cvt_pk_bf16_f32 v114, v114, v115
	v_cvt_pk_bf16_f32 v115, v116, v117
	v_cvt_pk_bf16_f32 v116, v118, v119
	v_cvt_pk_bf16_f32 v117, v120, v121
	global_store_dwordx4 v[248:249], v[114:117], off
	v_fmamk_f32 v239, v232, 0x3a800000, v158
	v_rsq_f32_e32 v121, v239
	s_nop 0
	v_mul_f32_e32 v120, 0xbfb8aa3b, v121
	v_pk_mul_f32 v[108:109], v[108:109], v[120:121] op_sel_hi:[1,0]
	v_pk_mul_f32 v[106:107], v[106:107], v[120:121] op_sel_hi:[1,0]
	v_pk_mul_f32 v[100:101], v[100:101], v[120:121] op_sel_hi:[1,0]
	v_pk_mul_f32 v[98:99], v[98:99], v[120:121] op_sel_hi:[1,0]
	v_exp_f32_e32 v106, v106
	v_exp_f32_e32 v107, v107
	v_exp_f32_e32 v108, v108
	v_exp_f32_e32 v109, v109
	v_exp_f32_e32 v98, v98
	v_exp_f32_e32 v99, v99
	v_exp_f32_e32 v100, v100
	v_exp_f32_e32 v101, v101
	v_fma_f32 v106, v106, v239, v239
	v_fma_f32 v107, v107, v239, v239
	v_fma_f32 v108, v108, v239, v239
	v_fma_f32 v109, v109, v239, v239
	v_fma_f32 v115, v98, v239, v239
	v_fma_f32 v120, v99, v239, v239
	v_fma_f32 v121, v100, v239, v239
	v_fma_f32 v125, v101, v239, v239
	v_rcp_f32_e32 v98, v106
	v_rcp_f32_e32 v99, v107
	v_rcp_f32_e32 v100, v108
	v_rcp_f32_e32 v101, v109
	v_rcp_f32_e32 v106, v115
	v_rcp_f32_e32 v107, v120
	v_rcp_f32_e32 v108, v121
	v_rcp_f32_e32 v109, v125
	v_pk_mul_f32 v[100:101], v[112:113], v[100:101]
	v_pk_mul_f32 v[98:99], v[110:111], v[98:99]
	v_pk_mul_f32 v[104:105], v[104:105], v[108:109]
	v_pk_mul_f32 v[102:103], v[102:103], v[106:107]
	s_mov_b32 s98, 0x16000
	v_lshl_add_u64 v[116:117], v[240:241], 0, s[98:99]
	v_cvt_pk_bf16_f32 v98, v98, v99
	v_cvt_pk_bf16_f32 v99, v100, v101
	v_cvt_pk_bf16_f32 v100, v102, v103
	v_cvt_pk_bf16_f32 v101, v104, v105
	global_store_dwordx4 v[116:117], v[98:101], off
	v_fmamk_f32 v239, v233, 0x3a800000, v158
	v_rsq_f32_e32 v105, v239
	s_nop 0
	v_mul_f32_e32 v104, 0xbfb8aa3b, v105
	v_pk_mul_f32 v[92:93], v[92:93], v[104:105] op_sel_hi:[1,0]
	v_pk_mul_f32 v[90:91], v[90:91], v[104:105] op_sel_hi:[1,0]
	v_pk_mul_f32 v[84:85], v[84:85], v[104:105] op_sel_hi:[1,0]
	v_pk_mul_f32 v[82:83], v[82:83], v[104:105] op_sel_hi:[1,0]
	v_exp_f32_e32 v90, v90
	v_exp_f32_e32 v91, v91
	v_exp_f32_e32 v92, v92
	v_exp_f32_e32 v93, v93
	v_exp_f32_e32 v82, v82
	v_exp_f32_e32 v83, v83
	v_exp_f32_e32 v84, v84
	v_exp_f32_e32 v85, v85
	v_fma_f32 v90, v90, v239, v239
	v_fma_f32 v91, v91, v239, v239
	v_fma_f32 v92, v92, v239, v239
	v_fma_f32 v93, v93, v239, v239
	v_fma_f32 v99, v82, v239, v239
	v_fma_f32 v104, v83, v239, v239
	v_fma_f32 v105, v84, v239, v239
	v_fma_f32 v107, v85, v239, v239
	v_rcp_f32_e32 v82, v90
	v_rcp_f32_e32 v83, v91
	v_rcp_f32_e32 v84, v92
	v_rcp_f32_e32 v85, v93
	v_rcp_f32_e32 v90, v99
	v_rcp_f32_e32 v91, v104
	v_rcp_f32_e32 v92, v105
	v_rcp_f32_e32 v93, v107
	v_pk_mul_f32 v[84:85], v[96:97], v[84:85]
	v_pk_mul_f32 v[82:83], v[94:95], v[82:83]
	v_pk_mul_f32 v[88:89], v[88:89], v[92:93]
	v_pk_mul_f32 v[86:87], v[86:87], v[90:91]
	s_mov_b32 s98, 0x2c000
	v_lshl_add_u64 v[100:101], v[240:241], 0, s[98:99]
	v_cvt_pk_bf16_f32 v82, v82, v83
	v_cvt_pk_bf16_f32 v83, v84, v85
	v_cvt_pk_bf16_f32 v84, v86, v87
	v_cvt_pk_bf16_f32 v85, v88, v89
	global_store_dwordx4 v[100:101], v[82:85], off
	s_nop 0
	s_nop 0
	s_mov_b32 s98, 0x42000
	v_lshl_add_u64 v[82:83], v[240:241], 0, s[98:99]
	v_fmamk_f32 v239, v234, 0x3a800000, v158
	v_rsq_f32_e32 v89, v239
	s_nop 0
	v_mul_f32_e32 v88, 0xbfb8aa3b, v89
	v_pk_mul_f32 v[76:77], v[76:77], v[88:89] op_sel_hi:[1,0]
	v_pk_mul_f32 v[74:75], v[74:75], v[88:89] op_sel_hi:[1,0]
	v_pk_mul_f32 v[68:69], v[68:69], v[88:89] op_sel_hi:[1,0]
	v_pk_mul_f32 v[66:67], v[66:67], v[88:89] op_sel_hi:[1,0]
	v_exp_f32_e32 v74, v74
	v_exp_f32_e32 v75, v75
	v_exp_f32_e32 v76, v76
	v_exp_f32_e32 v77, v77
	v_exp_f32_e32 v66, v66
	v_exp_f32_e32 v67, v67
	v_exp_f32_e32 v68, v68
	v_exp_f32_e32 v69, v69
	v_fma_f32 v74, v74, v239, v239
	v_fma_f32 v75, v75, v239, v239
	v_fma_f32 v76, v76, v239, v239
	v_fma_f32 v77, v77, v239, v239
	v_fma_f32 v85, v66, v239, v239
	v_fma_f32 v88, v67, v239, v239
	v_fma_f32 v89, v68, v239, v239
	v_fma_f32 v91, v69, v239, v239
	v_rcp_f32_e32 v66, v74
	v_rcp_f32_e32 v67, v75
	v_rcp_f32_e32 v68, v76
	v_rcp_f32_e32 v69, v77
	v_rcp_f32_e32 v74, v85
	v_rcp_f32_e32 v75, v88
	v_rcp_f32_e32 v76, v89
	v_rcp_f32_e32 v77, v91
	v_pk_mul_f32 v[68:69], v[80:81], v[68:69]
	v_pk_mul_f32 v[66:67], v[78:79], v[66:67]
	v_pk_mul_f32 v[72:73], v[72:73], v[76:77]
	v_pk_mul_f32 v[70:71], v[70:71], v[74:75]
	v_cvt_pk_bf16_f32 v66, v66, v67
	v_cvt_pk_bf16_f32 v67, v68, v69
	v_cvt_pk_bf16_f32 v68, v70, v71
	v_cvt_pk_bf16_f32 v69, v72, v73
	global_store_dwordx4 v[82:83], v[66:69], off
	v_fmamk_f32 v239, v235, 0x3a800000, v158
	v_rsq_f32_e32 v73, v239
	s_nop 0
	v_mul_f32_e32 v72, 0xbfb8aa3b, v73
	v_pk_mul_f32 v[60:61], v[60:61], v[72:73] op_sel_hi:[1,0]
	v_pk_mul_f32 v[58:59], v[58:59], v[72:73] op_sel_hi:[1,0]
	v_pk_mul_f32 v[52:53], v[52:53], v[72:73] op_sel_hi:[1,0]
	v_pk_mul_f32 v[50:51], v[50:51], v[72:73] op_sel_hi:[1,0]
	v_exp_f32_e32 v58, v58
	v_exp_f32_e32 v59, v59
	v_exp_f32_e32 v60, v60
	v_exp_f32_e32 v61, v61
	v_exp_f32_e32 v50, v50
	v_exp_f32_e32 v51, v51
	v_exp_f32_e32 v52, v52
	v_exp_f32_e32 v53, v53
	v_fma_f32 v58, v58, v239, v239
	v_fma_f32 v59, v59, v239, v239
	v_fma_f32 v60, v60, v239, v239
	v_fma_f32 v61, v61, v239, v239
	v_fma_f32 v67, v50, v239, v239
	v_fma_f32 v72, v51, v239, v239
	v_fma_f32 v73, v52, v239, v239
	v_fma_f32 v75, v53, v239, v239
	v_rcp_f32_e32 v50, v58
	v_rcp_f32_e32 v51, v59
	v_rcp_f32_e32 v52, v60
	v_rcp_f32_e32 v53, v61
	v_rcp_f32_e32 v58, v67
	v_rcp_f32_e32 v59, v72
	v_rcp_f32_e32 v60, v73
	v_rcp_f32_e32 v61, v75
	v_pk_mul_f32 v[52:53], v[64:65], v[52:53]
	v_pk_mul_f32 v[50:51], v[62:63], v[50:51]
	v_pk_mul_f32 v[56:57], v[56:57], v[60:61]
	v_pk_mul_f32 v[54:55], v[54:55], v[58:59]
	s_mov_b32 s98, 0xb0000
	v_lshl_add_u64 v[68:69], v[240:241], 0, s[98:99]
	v_cvt_pk_bf16_f32 v50, v50, v51
	v_cvt_pk_bf16_f32 v51, v52, v53
	v_cvt_pk_bf16_f32 v52, v54, v55
	v_cvt_pk_bf16_f32 v53, v56, v57
	global_store_dwordx4 v[68:69], v[50:53], off
	v_fmamk_f32 v239, v236, 0x3a800000, v158
	v_rsq_f32_e32 v57, v239
	s_nop 0
	v_mul_f32_e32 v56, 0xbfb8aa3b, v57
	v_pk_mul_f32 v[44:45], v[44:45], v[56:57] op_sel_hi:[1,0]
	v_pk_mul_f32 v[42:43], v[42:43], v[56:57] op_sel_hi:[1,0]
	v_pk_mul_f32 v[36:37], v[36:37], v[56:57] op_sel_hi:[1,0]
	v_pk_mul_f32 v[34:35], v[34:35], v[56:57] op_sel_hi:[1,0]
	v_exp_f32_e32 v42, v42
	v_exp_f32_e32 v43, v43
	v_exp_f32_e32 v44, v44
	v_exp_f32_e32 v45, v45
	v_exp_f32_e32 v34, v34
	v_exp_f32_e32 v35, v35
	v_exp_f32_e32 v36, v36
	v_exp_f32_e32 v37, v37
	v_fma_f32 v42, v42, v239, v239
	v_fma_f32 v43, v43, v239, v239
	v_fma_f32 v44, v44, v239, v239
	v_fma_f32 v45, v45, v239, v239
	v_fma_f32 v51, v34, v239, v239
	v_fma_f32 v56, v35, v239, v239
	v_fma_f32 v57, v36, v239, v239
	v_fma_f32 v59, v37, v239, v239
	v_rcp_f32_e32 v34, v42
	v_rcp_f32_e32 v35, v43
	v_rcp_f32_e32 v36, v44
	v_rcp_f32_e32 v37, v45
	v_rcp_f32_e32 v42, v51
	v_rcp_f32_e32 v43, v56
	v_rcp_f32_e32 v44, v57
	v_rcp_f32_e32 v45, v59
	v_pk_mul_f32 v[36:37], v[48:49], v[36:37]
	v_pk_mul_f32 v[34:35], v[46:47], v[34:35]
	v_pk_mul_f32 v[40:41], v[40:41], v[44:45]
	v_pk_mul_f32 v[38:39], v[38:39], v[42:43]
	s_mov_b32 s98, 0xc6000
	v_lshl_add_u64 v[52:53], v[240:241], 0, s[98:99]
	v_cvt_pk_bf16_f32 v34, v34, v35
	v_cvt_pk_bf16_f32 v35, v36, v37
	v_cvt_pk_bf16_f32 v36, v38, v39
	v_cvt_pk_bf16_f32 v37, v40, v41
	global_store_dwordx4 v[52:53], v[34:37], off
	v_fmamk_f32 v239, v237, 0x3a800000, v158
	v_rsq_f32_e32 v41, v239
	s_nop 0
	v_mul_f32_e32 v40, 0xbfb8aa3b, v41
	v_pk_mul_f32 v[28:29], v[28:29], v[40:41] op_sel_hi:[1,0]
	v_pk_mul_f32 v[26:27], v[26:27], v[40:41] op_sel_hi:[1,0]
	v_pk_mul_f32 v[20:21], v[20:21], v[40:41] op_sel_hi:[1,0]
	v_pk_mul_f32 v[18:19], v[18:19], v[40:41] op_sel_hi:[1,0]
	v_exp_f32_e32 v26, v26
	v_exp_f32_e32 v27, v27
	v_exp_f32_e32 v28, v28
	v_exp_f32_e32 v29, v29
	v_exp_f32_e32 v18, v18
	v_exp_f32_e32 v19, v19
	v_exp_f32_e32 v20, v20
	v_exp_f32_e32 v21, v21
	v_fma_f32 v26, v26, v239, v239
	v_fma_f32 v27, v27, v239, v239
	v_fma_f32 v28, v28, v239, v239
	v_fma_f32 v29, v29, v239, v239
	v_fma_f32 v35, v18, v239, v239
	v_fma_f32 v40, v19, v239, v239
	v_fma_f32 v41, v20, v239, v239
	v_fma_f32 v43, v21, v239, v239
	v_rcp_f32_e32 v18, v26
	v_rcp_f32_e32 v19, v27
	v_rcp_f32_e32 v20, v28
	v_rcp_f32_e32 v21, v29
	v_rcp_f32_e32 v26, v35
	v_rcp_f32_e32 v27, v40
	v_rcp_f32_e32 v28, v41
	v_rcp_f32_e32 v29, v43
	v_pk_mul_f32 v[20:21], v[32:33], v[20:21]
	v_pk_mul_f32 v[18:19], v[30:31], v[18:19]
	v_pk_mul_f32 v[24:25], v[24:25], v[28:29]
	v_pk_mul_f32 v[22:23], v[22:23], v[26:27]
	s_mov_b32 s98, 0xdc000
	v_lshl_add_u64 v[36:37], v[240:241], 0, s[98:99]
	v_cvt_pk_bf16_f32 v18, v18, v19
	v_cvt_pk_bf16_f32 v19, v20, v21
	v_cvt_pk_bf16_f32 v20, v22, v23
	v_cvt_pk_bf16_f32 v21, v24, v25
	global_store_dwordx4 v[36:37], v[18:21], off
	s_nop 0
	s_nop 0
	v_fmamk_f32 v239, v238, 0x3a800000, v158
	v_rsq_f32_e32 v21, v239
	s_nop 0
	v_mul_f32_e32 v20, 0xbfb8aa3b, v21
	v_pk_mul_f32 v[12:13], v[12:13], v[20:21] op_sel_hi:[1,0]
	v_pk_mul_f32 v[10:11], v[10:11], v[20:21] op_sel_hi:[1,0]
	v_pk_mul_f32 v[8:9], v[8:9], v[20:21] op_sel_hi:[1,0]
	v_pk_mul_f32 v[6:7], v[6:7], v[20:21] op_sel_hi:[1,0]
	v_exp_f32_e32 v10, v10
	v_exp_f32_e32 v11, v11
	v_exp_f32_e32 v12, v12
	v_exp_f32_e32 v13, v13
	v_exp_f32_e32 v6, v6
	v_exp_f32_e32 v7, v7
	v_exp_f32_e32 v8, v8
	v_exp_f32_e32 v9, v9
	v_fma_f32 v10, v10, v239, v239
	v_fma_f32 v11, v11, v239, v239
	v_fma_f32 v12, v12, v239, v239
	v_fma_f32 v13, v13, v239, v239
	v_fma_f32 v20, v6, v239, v239
	v_fma_f32 v21, v7, v239, v239
	v_fma_f32 v23, v8, v239, v239
	v_fma_f32 v24, v9, v239, v239
	v_rcp_f32_e32 v6, v10
	v_rcp_f32_e32 v7, v11
	v_rcp_f32_e32 v8, v12
	v_rcp_f32_e32 v9, v13
	v_rcp_f32_e32 v10, v20
	v_rcp_f32_e32 v11, v21
	v_rcp_f32_e32 v12, v23
	v_rcp_f32_e32 v13, v24
	v_pk_mul_f32 v[8:9], v[16:17], v[8:9]
	v_pk_mul_f32 v[6:7], v[14:15], v[6:7]
	v_pk_mul_f32 v[12:13], v[4:5], v[12:13]
	v_pk_mul_f32 v[4:5], v[2:3], v[10:11]
	s_mov_b32 s98, 0xf2000
	v_lshl_add_u64 v[18:19], v[240:241], 0, s[98:99]
	v_cvt_pk_bf16_f32 v2, v6, v7
	v_cvt_pk_bf16_f32 v3, v8, v9
	v_cvt_pk_bf16_f32 v4, v4, v5
	v_cvt_pk_bf16_f32 v5, v12, v13
	s_mov_b64 s[4:5], -1
	global_store_dwordx4 v[18:19], v[2:5], off
	s_cbranch_vccnz .LBB0_836
	s_andn2_b64 vcc, exec, s[8:9]
	s_cbranch_vccnz .LBB0_835
	s_barrier
	s_branch .LBB0_835

.Lz_post_p8b:
	s_lshl_b32 s25, s46, 8
	v_add_u32_e32 v148, s25, v150
	v_ashrrev_i32_e32 v149, 31, v148
	v_lshl_add_u64 v[244:245], v[148:149], 2, s[8:9]
	global_load_dword v149, v[244:245], off
	global_load_dword v232, v[244:245], off offset:64
	global_load_dword v233, v[244:245], off offset:128
	global_load_dword v234, v[244:245], off offset:192
	global_load_dword v235, v[244:245], off offset:512
	global_load_dword v236, v[244:245], off offset:576
	global_load_dword v237, v[244:245], off offset:640
	global_load_dword v238, v[244:245], off offset:704
	v_pk_mul_f32 v[128:129], v[120:121], v[128:129]
	v_pk_mul_f32 v[126:127], v[118:119], v[126:127]
	v_pk_mul_f32 v[124:125], v[116:117], v[124:125]
	v_pk_mul_f32 v[244:245], v[114:115], v[122:123]
	s_lshl_b32 s46, s47, 7
	v_mov_b64_e32 v[122:123], s[10:11]
	s_ashr_i32 s47, s46, 31
	v_mad_i64_i32 v[248:249], s[48:49], v148, s68, v[122:123]
	s_lshl_b64 s[46:47], s[46:47], 1
	v_lshl_add_u64 v[248:249], v[248:249], 0, s[46:47]
	v_lshl_add_u64 v[248:249], v[248:249], 0, v[138:139]
	v_mov_b64_e32 v[240:241], v[248:249]
	s_mov_b32 s99, 0
	v_pk_mul_f32 v[112:113], v[108:109], v[112:113]
	v_pk_mul_f32 v[110:111], v[106:107], v[110:111]
	v_pk_mul_f32 v[104:105], v[100:101], v[104:105]
	v_pk_mul_f32 v[102:103], v[98:99], v[102:103]
	v_pk_mul_f32 v[96:97], v[92:93], v[96:97]
	v_pk_mul_f32 v[94:95], v[90:91], v[94:95]
	v_pk_mul_f32 v[88:89], v[84:85], v[88:89]
	v_pk_mul_f32 v[86:87], v[82:83], v[86:87]
	v_pk_mul_f32 v[80:81], v[76:77], v[80:81]
	v_pk_mul_f32 v[78:79], v[74:75], v[78:79]
	v_pk_mul_f32 v[72:73], v[68:69], v[72:73]
	v_pk_mul_f32 v[70:71], v[66:67], v[70:71]
	v_pk_mul_f32 v[64:65], v[60:61], v[64:65]
	v_pk_mul_f32 v[62:63], v[58:59], v[62:63]
	v_pk_mul_f32 v[56:57], v[52:53], v[56:57]
	v_pk_mul_f32 v[54:55], v[50:51], v[54:55]
	v_pk_mul_f32 v[48:49], v[44:45], v[48:49]
	v_pk_mul_f32 v[46:47], v[42:43], v[46:47]
	v_pk_mul_f32 v[40:41], v[36:37], v[40:41]
	v_pk_mul_f32 v[38:39], v[34:35], v[38:39]
	v_pk_mul_f32 v[32:33], v[28:29], v[32:33]
	v_pk_mul_f32 v[30:31], v[26:27], v[30:31]
	v_pk_mul_f32 v[24:25], v[20:21], v[24:25]
	v_pk_mul_f32 v[22:23], v[18:19], v[22:23]
	v_pk_mul_f32 v[16:17], v[12:13], v[16:17]
	v_pk_mul_f32 v[14:15], v[10:11], v[14:15]
	v_pk_mul_f32 v[4:5], v[8:9], v[4:5]
	v_pk_mul_f32 v[2:3], v[6:7], v[2:3]
	s_and_b64 vcc, exec, s[16:17]
	s_cbranch_vccz .LBB0_1133
	s_barrier
.LBB0_1133:
	ds_read_b128 v[160:163], v155
	ds_read_b128 v[164:167], v155 offset:1024
	ds_read_b128 v[168:171], v155 offset:2048
	ds_read_b128 v[172:175], v155 offset:3072
	ds_read_b128 v[176:179], v156
	ds_read_b128 v[180:183], v156 offset:1024
	ds_read_b128 v[184:187], v156 offset:2048
	ds_read_b128 v[188:191], v156 offset:3072
	ds_read_b128 v[192:195], v157
	ds_read_b128 v[196:199], v157 offset:1024
	ds_read_b128 v[200:203], v157 offset:2048
	ds_read_b128 v[204:207], v157 offset:3072
	ds_read_b128 v[208:211], v157 offset:4096
	ds_read_b128 v[212:215], v157 offset:5120
	ds_read_b128 v[216:219], v157 offset:6144
	ds_read_b128 v[220:223], v157 offset:7168
	s_andn2_b64 vcc, exec, s[4:5]
	s_waitcnt vmcnt(0)
	v_fmamk_f32 v239, v149, 0x3a800000, v158
	v_rsq_f32_e32 v149, v239
	s_nop 0
	v_mul_f32_e32 v252, 0xbfb8aa3b, v149
	v_pk_mul_f32 v[120:121], v[120:121], v[252:253] op_sel_hi:[1,0]
	v_pk_mul_f32 v[118:119], v[118:119], v[252:253] op_sel_hi:[1,0]
	v_pk_mul_f32 v[116:117], v[116:117], v[252:253] op_sel_hi:[1,0]
	v_pk_mul_f32 v[114:115], v[114:115], v[252:253] op_sel_hi:[1,0]
	v_exp_f32_e32 v118, v118
	v_exp_f32_e32 v119, v119
	v_exp_f32_e32 v120, v120
	v_exp_f32_e32 v121, v121
	v_exp_f32_e32 v114, v114
	v_exp_f32_e32 v115, v115
	v_exp_f32_e32 v116, v116
	v_exp_f32_e32 v117, v117
	v_fma_f32 v118, v118, v239, v239
	v_fma_f32 v119, v119, v239, v239
	v_fma_f32 v120, v120, v239, v239
	v_fma_f32 v121, v121, v239, v239
	v_fma_f32 v149, v114, v239, v239
	v_fma_f32 v159, v115, v239, v239
	v_fma_f32 v247, v116, v239, v239
	v_fma_f32 v252, v117, v239, v239
	v_rcp_f32_e32 v114, v118
	v_rcp_f32_e32 v115, v119
	v_rcp_f32_e32 v116, v120
	v_rcp_f32_e32 v117, v121
	v_rcp_f32_e32 v118, v149
	v_rcp_f32_e32 v119, v159
	v_rcp_f32_e32 v120, v247
	v_rcp_f32_e32 v121, v252
	v_pk_mul_f32 v[116:117], v[128:129], v[116:117]
	v_pk_mul_f32 v[114:115], v[126:127], v[114:115]
	v_pk_mul_f32 v[120:121], v[124:125], v[120:121]
	v_pk_mul_f32 v[118:119], v[244:245], v[118:119]
	v_cvt_pk_bf16_f32 v114, v114, v115
	v_cvt_pk_bf16_f32 v115, v116, v117
	v_cvt_pk_bf16_f32 v116, v118, v119
	v_cvt_pk_bf16_f32 v117, v120, v121
	global_store_dwordx4 v[248:249], v[114:117], off
	v_fmamk_f32 v239, v232, 0x3a800000, v158
	v_rsq_f32_e32 v121, v239
	s_nop 0
	v_mul_f32_e32 v120, 0xbfb8aa3b, v121
	v_pk_mul_f32 v[108:109], v[108:109], v[120:121] op_sel_hi:[1,0]
	v_pk_mul_f32 v[106:107], v[106:107], v[120:121] op_sel_hi:[1,0]
	v_pk_mul_f32 v[100:101], v[100:101], v[120:121] op_sel_hi:[1,0]
	v_pk_mul_f32 v[98:99], v[98:99], v[120:121] op_sel_hi:[1,0]
	v_exp_f32_e32 v106, v106
	v_exp_f32_e32 v107, v107
	v_exp_f32_e32 v108, v108
	v_exp_f32_e32 v109, v109
	v_exp_f32_e32 v98, v98
	v_exp_f32_e32 v99, v99
	v_exp_f32_e32 v100, v100
	v_exp_f32_e32 v101, v101
	v_fma_f32 v106, v106, v239, v239
	v_fma_f32 v107, v107, v239, v239
	v_fma_f32 v108, v108, v239, v239
	v_fma_f32 v109, v109, v239, v239
	v_fma_f32 v115, v98, v239, v239
	v_fma_f32 v120, v99, v239, v239
	v_fma_f32 v121, v100, v239, v239
	v_fma_f32 v125, v101, v239, v239
	v_rcp_f32_e32 v98, v106
	v_rcp_f32_e32 v99, v107
	v_rcp_f32_e32 v100, v108
	v_rcp_f32_e32 v101, v109
	v_rcp_f32_e32 v106, v115
	v_rcp_f32_e32 v107, v120
	v_rcp_f32_e32 v108, v121
	v_rcp_f32_e32 v109, v125
	v_pk_mul_f32 v[100:101], v[112:113], v[100:101]
	v_pk_mul_f32 v[98:99], v[110:111], v[98:99]
	v_pk_mul_f32 v[104:105], v[104:105], v[108:109]
	v_pk_mul_f32 v[102:103], v[102:103], v[106:107]
	s_mov_b32 s98, 0x16000
	v_lshl_add_u64 v[116:117], v[240:241], 0, s[98:99]
	v_cvt_pk_bf16_f32 v98, v98, v99
	v_cvt_pk_bf16_f32 v99, v100, v101
	v_cvt_pk_bf16_f32 v100, v102, v103
	v_cvt_pk_bf16_f32 v101, v104, v105
	global_store_dwordx4 v[116:117], v[98:101], off
	v_fmamk_f32 v239, v233, 0x3a800000, v158
	v_rsq_f32_e32 v105, v239
	s_nop 0
	v_mul_f32_e32 v104, 0xbfb8aa3b, v105
	v_pk_mul_f32 v[92:93], v[92:93], v[104:105] op_sel_hi:[1,0]
	v_pk_mul_f32 v[90:91], v[90:91], v[104:105] op_sel_hi:[1,0]
	v_pk_mul_f32 v[84:85], v[84:85], v[104:105] op_sel_hi:[1,0]
	v_pk_mul_f32 v[82:83], v[82:83], v[104:105] op_sel_hi:[1,0]
	v_exp_f32_e32 v90, v90
	v_exp_f32_e32 v91, v91
	v_exp_f32_e32 v92, v92
	v_exp_f32_e32 v93, v93
	v_exp_f32_e32 v82, v82
	v_exp_f32_e32 v83, v83
	v_exp_f32_e32 v84, v84
	v_exp_f32_e32 v85, v85
	v_fma_f32 v90, v90, v239, v239
	v_fma_f32 v91, v91, v239, v239
	v_fma_f32 v92, v92, v239, v239
	v_fma_f32 v93, v93, v239, v239
	v_fma_f32 v99, v82, v239, v239
	v_fma_f32 v104, v83, v239, v239
	v_fma_f32 v105, v84, v239, v239
	v_fma_f32 v107, v85, v239, v239
	v_rcp_f32_e32 v82, v90
	v_rcp_f32_e32 v83, v91
	v_rcp_f32_e32 v84, v92
	v_rcp_f32_e32 v85, v93
	v_rcp_f32_e32 v90, v99
	v_rcp_f32_e32 v91, v104
	v_rcp_f32_e32 v92, v105
	v_rcp_f32_e32 v93, v107
	v_pk_mul_f32 v[84:85], v[96:97], v[84:85]
	v_pk_mul_f32 v[82:83], v[94:95], v[82:83]
	v_pk_mul_f32 v[88:89], v[88:89], v[92:93]
	v_pk_mul_f32 v[86:87], v[86:87], v[90:91]
	s_mov_b32 s98, 0x2c000
	v_lshl_add_u64 v[100:101], v[240:241], 0, s[98:99]
	v_cvt_pk_bf16_f32 v82, v82, v83
	v_cvt_pk_bf16_f32 v83, v84, v85
	v_cvt_pk_bf16_f32 v84, v86, v87
	v_cvt_pk_bf16_f32 v85, v88, v89
	global_store_dwordx4 v[100:101], v[82:85], off
	s_nop 0
	s_nop 0
	s_mov_b32 s98, 0x42000
	v_lshl_add_u64 v[82:83], v[240:241], 0, s[98:99]
	v_fmamk_f32 v239, v234, 0x3a800000, v158
	v_rsq_f32_e32 v89, v239
	s_nop 0
	v_mul_f32_e32 v88, 0xbfb8aa3b, v89
	v_pk_mul_f32 v[76:77], v[76:77], v[88:89] op_sel_hi:[1,0]
	v_pk_mul_f32 v[74:75], v[74:75], v[88:89] op_sel_hi:[1,0]
	v_pk_mul_f32 v[68:69], v[68:69], v[88:89] op_sel_hi:[1,0]
	v_pk_mul_f32 v[66:67], v[66:67], v[88:89] op_sel_hi:[1,0]
	v_exp_f32_e32 v74, v74
	v_exp_f32_e32 v75, v75
	v_exp_f32_e32 v76, v76
	v_exp_f32_e32 v77, v77
	v_exp_f32_e32 v66, v66
	v_exp_f32_e32 v67, v67
	v_exp_f32_e32 v68, v68
	v_exp_f32_e32 v69, v69
	v_fma_f32 v74, v74, v239, v239
	v_fma_f32 v75, v75, v239, v239
	v_fma_f32 v76, v76, v239, v239
	v_fma_f32 v77, v77, v239, v239
	v_fma_f32 v85, v66, v239, v239
	v_fma_f32 v88, v67, v239, v239
	v_fma_f32 v89, v68, v239, v239
	v_fma_f32 v91, v69, v239, v239
	v_rcp_f32_e32 v66, v74
	v_rcp_f32_e32 v67, v75
	v_rcp_f32_e32 v68, v76
	v_rcp_f32_e32 v69, v77
	v_rcp_f32_e32 v74, v85
	v_rcp_f32_e32 v75, v88
	v_rcp_f32_e32 v76, v89
	v_rcp_f32_e32 v77, v91
	v_pk_mul_f32 v[68:69], v[80:81], v[68:69]
	v_pk_mul_f32 v[66:67], v[78:79], v[66:67]
	v_pk_mul_f32 v[72:73], v[72:73], v[76:77]
	v_pk_mul_f32 v[70:71], v[70:71], v[74:75]
	v_cvt_pk_bf16_f32 v66, v66, v67
	v_cvt_pk_bf16_f32 v67, v68, v69
	v_cvt_pk_bf16_f32 v68, v70, v71
	v_cvt_pk_bf16_f32 v69, v72, v73
	global_store_dwordx4 v[82:83], v[66:69], off
	v_fmamk_f32 v239, v235, 0x3a800000, v158
	v_rsq_f32_e32 v73, v239
	s_nop 0
	v_mul_f32_e32 v72, 0xbfb8aa3b, v73
	v_pk_mul_f32 v[60:61], v[60:61], v[72:73] op_sel_hi:[1,0]
	v_pk_mul_f32 v[58:59], v[58:59], v[72:73] op_sel_hi:[1,0]
	v_pk_mul_f32 v[52:53], v[52:53], v[72:73] op_sel_hi:[1,0]
	v_pk_mul_f32 v[50:51], v[50:51], v[72:73] op_sel_hi:[1,0]
	v_exp_f32_e32 v58, v58
	v_exp_f32_e32 v59, v59
	v_exp_f32_e32 v60, v60
	v_exp_f32_e32 v61, v61
	v_exp_f32_e32 v50, v50
	v_exp_f32_e32 v51, v51
	v_exp_f32_e32 v52, v52
	v_exp_f32_e32 v53, v53
	v_fma_f32 v58, v58, v239, v239
	v_fma_f32 v59, v59, v239, v239
	v_fma_f32 v60, v60, v239, v239
	v_fma_f32 v61, v61, v239, v239
	v_fma_f32 v67, v50, v239, v239
	v_fma_f32 v72, v51, v239, v239
	v_fma_f32 v73, v52, v239, v239
	v_fma_f32 v75, v53, v239, v239
	v_rcp_f32_e32 v50, v58
	v_rcp_f32_e32 v51, v59
	v_rcp_f32_e32 v52, v60
	v_rcp_f32_e32 v53, v61
	v_rcp_f32_e32 v58, v67
	v_rcp_f32_e32 v59, v72
	v_rcp_f32_e32 v60, v73
	v_rcp_f32_e32 v61, v75
	v_pk_mul_f32 v[52:53], v[64:65], v[52:53]
	v_pk_mul_f32 v[50:51], v[62:63], v[50:51]
	v_pk_mul_f32 v[56:57], v[56:57], v[60:61]
	v_pk_mul_f32 v[54:55], v[54:55], v[58:59]
	s_mov_b32 s98, 0xb0000
	v_lshl_add_u64 v[68:69], v[240:241], 0, s[98:99]
	v_cvt_pk_bf16_f32 v50, v50, v51
	v_cvt_pk_bf16_f32 v51, v52, v53
	v_cvt_pk_bf16_f32 v52, v54, v55
	v_cvt_pk_bf16_f32 v53, v56, v57
	global_store_dwordx4 v[68:69], v[50:53], off
	v_fmamk_f32 v239, v236, 0x3a800000, v158
	v_rsq_f32_e32 v57, v239
	s_nop 0
	v_mul_f32_e32 v56, 0xbfb8aa3b, v57
	v_pk_mul_f32 v[44:45], v[44:45], v[56:57] op_sel_hi:[1,0]
	v_pk_mul_f32 v[42:43], v[42:43], v[56:57] op_sel_hi:[1,0]
	v_pk_mul_f32 v[36:37], v[36:37], v[56:57] op_sel_hi:[1,0]
	v_pk_mul_f32 v[34:35], v[34:35], v[56:57] op_sel_hi:[1,0]
	v_exp_f32_e32 v42, v42
	v_exp_f32_e32 v43, v43
	v_exp_f32_e32 v44, v44
	v_exp_f32_e32 v45, v45
	v_exp_f32_e32 v34, v34
	v_exp_f32_e32 v35, v35
	v_exp_f32_e32 v36, v36
	v_exp_f32_e32 v37, v37
	v_fma_f32 v42, v42, v239, v239
	v_fma_f32 v43, v43, v239, v239
	v_fma_f32 v44, v44, v239, v239
	v_fma_f32 v45, v45, v239, v239
	v_fma_f32 v51, v34, v239, v239
	v_fma_f32 v56, v35, v239, v239
	v_fma_f32 v57, v36, v239, v239
	v_fma_f32 v59, v37, v239, v239
	v_rcp_f32_e32 v34, v42
	v_rcp_f32_e32 v35, v43
	v_rcp_f32_e32 v36, v44
	v_rcp_f32_e32 v37, v45
	v_rcp_f32_e32 v42, v51
	v_rcp_f32_e32 v43, v56
	v_rcp_f32_e32 v44, v57
	v_rcp_f32_e32 v45, v59
	v_pk_mul_f32 v[36:37], v[48:49], v[36:37]
	v_pk_mul_f32 v[34:35], v[46:47], v[34:35]
	v_pk_mul_f32 v[40:41], v[40:41], v[44:45]
	v_pk_mul_f32 v[38:39], v[38:39], v[42:43]
	s_mov_b32 s98, 0xc6000
	v_lshl_add_u64 v[52:53], v[240:241], 0, s[98:99]
	v_cvt_pk_bf16_f32 v34, v34, v35
	v_cvt_pk_bf16_f32 v35, v36, v37
	v_cvt_pk_bf16_f32 v36, v38, v39
	v_cvt_pk_bf16_f32 v37, v40, v41
	global_store_dwordx4 v[52:53], v[34:37], off
	v_fmamk_f32 v239, v237, 0x3a800000, v158
	v_rsq_f32_e32 v41, v239
	s_nop 0
	v_mul_f32_e32 v40, 0xbfb8aa3b, v41
	v_pk_mul_f32 v[28:29], v[28:29], v[40:41] op_sel_hi:[1,0]
	v_pk_mul_f32 v[26:27], v[26:27], v[40:41] op_sel_hi:[1,0]
	v_pk_mul_f32 v[20:21], v[20:21], v[40:41] op_sel_hi:[1,0]
	v_pk_mul_f32 v[18:19], v[18:19], v[40:41] op_sel_hi:[1,0]
	v_exp_f32_e32 v26, v26
	v_exp_f32_e32 v27, v27
	v_exp_f32_e32 v28, v28
	v_exp_f32_e32 v29, v29
	v_exp_f32_e32 v18, v18
	v_exp_f32_e32 v19, v19
	v_exp_f32_e32 v20, v20
	v_exp_f32_e32 v21, v21
	v_fma_f32 v26, v26, v239, v239
	v_fma_f32 v27, v27, v239, v239
	v_fma_f32 v28, v28, v239, v239
	v_fma_f32 v29, v29, v239, v239
	v_fma_f32 v35, v18, v239, v239
	v_fma_f32 v40, v19, v239, v239
	v_fma_f32 v41, v20, v239, v239
	v_fma_f32 v43, v21, v239, v239
	v_rcp_f32_e32 v18, v26
	v_rcp_f32_e32 v19, v27
	v_rcp_f32_e32 v20, v28
	v_rcp_f32_e32 v21, v29
	v_rcp_f32_e32 v26, v35
	v_rcp_f32_e32 v27, v40
	v_rcp_f32_e32 v28, v41
	v_rcp_f32_e32 v29, v43
	v_pk_mul_f32 v[20:21], v[32:33], v[20:21]
	v_pk_mul_f32 v[18:19], v[30:31], v[18:19]
	v_pk_mul_f32 v[24:25], v[24:25], v[28:29]
	v_pk_mul_f32 v[22:23], v[22:23], v[26:27]
	s_mov_b32 s98, 0xdc000
	v_lshl_add_u64 v[36:37], v[240:241], 0, s[98:99]
	v_cvt_pk_bf16_f32 v18, v18, v19
	v_cvt_pk_bf16_f32 v19, v20, v21
	v_cvt_pk_bf16_f32 v20, v22, v23
	v_cvt_pk_bf16_f32 v21, v24, v25
	global_store_dwordx4 v[36:37], v[18:21], off
	s_nop 0
	s_nop 0
	v_fmamk_f32 v239, v238, 0x3a800000, v158
	v_rsq_f32_e32 v21, v239
	s_nop 0
	v_mul_f32_e32 v20, 0xbfb8aa3b, v21
	v_pk_mul_f32 v[12:13], v[12:13], v[20:21] op_sel_hi:[1,0]
	v_pk_mul_f32 v[10:11], v[10:11], v[20:21] op_sel_hi:[1,0]
	v_pk_mul_f32 v[8:9], v[8:9], v[20:21] op_sel_hi:[1,0]
	v_pk_mul_f32 v[6:7], v[6:7], v[20:21] op_sel_hi:[1,0]
	v_exp_f32_e32 v10, v10
	v_exp_f32_e32 v11, v11
	v_exp_f32_e32 v12, v12
	v_exp_f32_e32 v13, v13
	v_exp_f32_e32 v6, v6
	v_exp_f32_e32 v7, v7
	v_exp_f32_e32 v8, v8
	v_exp_f32_e32 v9, v9
	v_fma_f32 v10, v10, v239, v239
	v_fma_f32 v11, v11, v239, v239
	v_fma_f32 v12, v12, v239, v239
	v_fma_f32 v13, v13, v239, v239
	v_fma_f32 v20, v6, v239, v239
	v_fma_f32 v21, v7, v239, v239
	v_fma_f32 v23, v8, v239, v239
	v_fma_f32 v24, v9, v239, v239
	v_rcp_f32_e32 v6, v10
	v_rcp_f32_e32 v7, v11
	v_rcp_f32_e32 v8, v12
	v_rcp_f32_e32 v9, v13
	v_rcp_f32_e32 v10, v20
	v_rcp_f32_e32 v11, v21
	v_rcp_f32_e32 v12, v23
	v_rcp_f32_e32 v13, v24
	v_pk_mul_f32 v[8:9], v[16:17], v[8:9]
	v_pk_mul_f32 v[6:7], v[14:15], v[6:7]
	v_pk_mul_f32 v[12:13], v[4:5], v[12:13]
	v_pk_mul_f32 v[4:5], v[2:3], v[10:11]
	s_mov_b32 s98, 0xf2000
	v_lshl_add_u64 v[18:19], v[240:241], 0, s[98:99]
	v_cvt_pk_bf16_f32 v2, v6, v7
	v_cvt_pk_bf16_f32 v3, v8, v9
	v_cvt_pk_bf16_f32 v4, v4, v5
	v_cvt_pk_bf16_f32 v5, v12, v13
	s_mov_b64 s[4:5], -1
	global_store_dwordx4 v[18:19], v[2:5], off
	s_cbranch_vccnz .LBB0_1126
	s_andn2_b64 vcc, exec, s[6:7]
	s_cbranch_vccnz .LBB0_1125
	s_barrier
	s_branch .LBB0_1125
